# attention unit queues: one coherent load of the 8 queue counters skips exhausted queues instead of 7 serial failing atomics at the phase tail
# speedup vs baseline: 1.0267x; 1.0124x over previous
.LBB0_81:
	s_add_i32 s1, s1, 1
	s_cmp_eq_u32 s1, 8
	s_cbranch_scc1 .LBB0_208
	s_and_saveexec_b64 s[2:3], s[60:61]
	s_cbranch_execz .Lqs_skip
	s_mov_b64 exec, 0xff
	v_readlane_b32 s0, v253, 0
	v_readlane_b32 s13, v255, 35
	s_mov_b32 s12, s17
	v_add_u32_e32 v2, s0, v205
	v_and_b32_e32 v2, 7, v2
	v_lshlrev_b32_e32 v2, 2, v2
	s_nop 4
	global_load_dword v0, v2, s[12:13] sc0 sc1
	s_waitcnt vmcnt(0)
	v_cmp_gt_u32_e32 vcc, s25, v0
	s_nop 1
	s_and_b32 s0, vcc_lo, 0xff
	s_lshl_b32 s12, 1, s1
	s_add_i32 s12, s12, -1
	s_andn2_b32 s0, s0, s12
	s_ff1_i32_b32 s0, s0
	s_cmp_lt_i32 s0, 0
	s_cselect_b32 s0, 8, s0
	s_mov_b64 exec, 1
	v_mov_b32_e32 v2, s0
	ds_write_b32 v202, v2
.Lqs_skip:
	s_or_b64 exec, exec, s[2:3]
	s_waitcnt lgkmcnt(0)
	s_barrier
	ds_read_b32 v0, v202
	s_waitcnt lgkmcnt(0)
	s_barrier
	v_readfirstlane_b32 s1, v0
	s_nop 0
	s_cmp_ge_u32 s1, 8
	s_cbranch_scc1 .LBB0_208
